# v91 + P2: rot-0 workgroups (S5 first) run rot-2's order (HGRN2 chunk pass first)
# baseline (speedup 1.0000x reference)
; #define STAMP(i) do { if (F.bid == AMP_BLK && F.tid == 0) { const unsigned long long t_ = __builtin_amdgcn_s_memrealtime(); volatile LAS unsigned* M_ = (volatile LAS unsigned*)(F.lds + LDS_BYTES - 512); M_[64 + 2 * (i)] = (unsigned)t_; M_[65 + 2 * (i)] = (unsigned)(t_ >> 32); } } while (0)
; #define STAMP(i) do { } while (0)
; __global__ void __launch_bounds__(NWAVES * 64, 2) mk_fwd(Args args) {
;     ...
;     if (IN(2)) {
;         const int nper = (1024 + F.G - 1) / F.G, rot = F.bid % 3;
;         STAMP(30);
;         if (rot == 0) {
;             STAMP(4);
;             for (int it = F.bid; it < 256; it += F.G) s5_item(F, it);
;             STAMP(5);
;             hgA_loop(F, 0, nper);
;             STAMP(6);
;             hgrn_sample_loop(F);
;             STAMP(7);
;         } else if (rot == 1) {
;             hgrn_sample_loop(F);
;             hgA_loop(F, 0, nper);
;             __syncthreads();
;             for (int it = F.bid; it < 256; it += F.G) s5_item(F, it);
;         } else {
;             hgA_loop(F, 0, nper);
;             __syncthreads();
;             for (int it = F.bid; it < 256; it += F.G) s5_item(F, it);
;             hgrn_sample_loop(F);
;         }
.LBB0_274:
	v_readlane_b32 s0, v238, 0
	v_readlane_b32 s1, v238, 1
	s_cmp_lt_i32 s0, 3
	s_cselect_b64 s[0:1], -1, 0
	s_add_u32 s6, s50, 0xa300000
	s_addc_u32 s7, s51, 0
	v_writelane_b32 v238, s6, 47
	s_and_b64 s[0:1], s[0:1], s[4:5]
	s_nop 0
	v_writelane_b32 v238, s7, 48
	v_writelane_b32 v238, s0, 49
	s_andn2_b64 vcc, exec, s[0:1]
	s_nop 0
	v_writelane_b32 v238, s1, 50
	s_cbranch_vccnz .LBB0_551
	s_abs_i32 s0, s52
	v_cvt_f32_u32_e32 v2, s0
	s_sub_i32 s4, 0, s0
	s_add_i32 s3, s52, 0x3ff
	s_ashr_i32 s1, s3, 31
	v_rcp_iflag_f32_e32 v2, v2
	s_abs_i32 s3, s3
	s_ashr_i32 s53, s52, 31
	s_xor_b32 s1, s1, s53
	v_mul_f32_e32 v2, 0x4f7ffffe, v2
	v_cvt_u32_f32_e32 v2, v2
	s_nop 0
	v_readfirstlane_b32 s5, v2
	s_mul_i32 s4, s4, s5
	s_mul_hi_u32 s4, s5, s4
	s_add_i32 s5, s5, s4
	s_mul_hi_u32 s4, s3, s5
	s_mul_i32 s5, s4, s0
	s_sub_i32 s3, s3, s5
	s_add_i32 s5, s4, 1
	s_sub_i32 s6, s3, s0
	s_cmp_ge_u32 s3, s0
	s_cselect_b32 s4, s5, s4
	s_cselect_b32 s3, s6, s3
	s_add_i32 s5, s4, 1
	s_cmp_ge_u32 s3, s0
	s_cselect_b32 s0, s5, s4
	s_xor_b32 s0, s0, s1
	s_sub_i32 s0, s0, s1
	v_writelane_b32 v238, s0, 51
	s_mul_hi_i32 s0, s2, 0x55555556
	s_lshr_b32 s1, s0, 31
	s_add_i32 s0, s0, s1
	s_mul_i32 s0, s0, 3
	s_sub_i32 s0, s2, s0
	s_cmp_eq_u32 s0, 0
	s_cselect_b32 s0, 2, s0
	s_mov_b64 s[4:5], -1
	v_writelane_b32 v238, s0, 52
	s_cmp_lt_i32 s0, 1
	s_mov_b64 s[0:1], 0
	v_writelane_b32 v238, s96, 53
	s_cbranch_scc1 .LBB0_290
	v_readlane_b32 s0, v238, 52
	s_cmp_eq_u32 s0, 1
	s_mov_b64 s[0:1], -1
	s_cbranch_scc0 .LBB0_372
	s_cmpk_lt_i32 s2, 0x200
	s_cbranch_scc0 .LBB0_293
; #define GAS __attribute__((address_space(1)))
; #define LAS __attribute__((address_space(3)))
; __device__ __forceinline__ void hgrn_sample_loop(Frame& F) {
;     const int tid = F.tid;
;     LAS float* Qs = (LAS float*)(F.lds + LX_Q); LAS float* K2 = (LAS float*)(F.lds + LX_K2); LAS float* QT = (LAS float*)(F.lds + LX_QT); LAS float* K3T = (LAS float*)(F.lds + LX_K3T); LAS float* Vs = (LAS float*)(F.lds + LX_V);
;     LAS float* DEC = (LAS float*)(F.lds + LX_DEC); LAS float* ATT = (LAS float*)(F.lds + LX_ATT); LAS float* OP = (LAS float*)(F.lds + LX_OP); LAS float* OT = (LAS float*)(F.lds + LX_OT);
;     const bf16* PB = (const bf16*)(F.ws + WS_PB); const float* FZ = (const float*)(F.ws + WS_FZ); bf16* MIX = (bf16*)(F.ws + WS_MIX);
;     const int v4 = (tid & 31) * 4, kg = tid >> 5;
;     int idx = F.bid; if (idx >= SB_B * HH) return;
;     f32x4 s0[8];
; #pragma unroll
;     for (int j = 0; j < 8; ++j) s0[j] = *(const GAS f32x4*)(F.in[4] + (size_t)idx * HD * HD + (size_t)(8 * kg + j) * HD + v4);
	s_ashr_i32 s3, s2, 31
	v_readlane_b32 s60, v238, 4
	v_lshrrev_b32_e32 v36, 5, v0
	s_lshl_b64 s[4:5], s[2:3], 16
	v_readlane_b32 s68, v238, 12
	v_lshlrev_b32_e32 v4, 3, v36
	v_mov_b32_e32 v135, 0
	v_readlane_b32 s69, v238, 13
	s_add_u32 s0, s68, s4
	v_lshlrev_b32_e32 v6, 4, v0
	v_or_b32_e32 v37, 1, v4
	v_or_b32_e32 v38, 2, v4
	v_or_b32_e32 v39, 3, v4
	v_or_b32_e32 v40, 4, v4
	v_or_b32_e32 v41, 5, v4
	v_or_b32_e32 v42, 6, v4
	v_or_b32_e32 v43, 7, v4
	s_addc_u32 s1, s69, s5
	v_and_b32_e32 v34, 0x1f0, v6
	v_mov_b32_e32 v35, v135
	v_lshlrev_b32_e32 v132, 12, v36
	v_mov_b32_e32 v133, v135
	v_lshlrev_b32_e32 v134, 9, v37
	v_lshlrev_b32_e32 v18, 9, v38
	v_mov_b32_e32 v19, v135
	v_lshlrev_b32_e32 v20, 9, v39
	v_mov_b32_e32 v21, v135
	v_lshlrev_b32_e32 v10, 9, v40
	v_mov_b32_e32 v11, v135
	v_lshlrev_b32_e32 v12, 9, v41
	v_mov_b32_e32 v13, v135
	v_lshlrev_b32_e32 v2, 9, v42
	v_mov_b32_e32 v3, v135
	v_lshlrev_b32_e32 v4, 9, v43
	v_mov_b32_e32 v5, v135
	v_lshl_add_u64 v[26:27], s[0:1], 0, v[34:35]
	v_lshl_add_u64 v[4:5], v[26:27], 0, v[4:5]
	v_lshl_add_u64 v[6:7], v[26:27], 0, v[2:3]
	v_lshl_add_u64 v[12:13], v[26:27], 0, v[12:13]
	v_lshl_add_u64 v[14:15], v[26:27], 0, v[10:11]
	v_lshl_add_u64 v[20:21], v[26:27], 0, v[20:21]
	v_lshl_add_u64 v[22:23], v[26:27], 0, v[18:19]
	v_lshl_add_u64 v[28:29], v[26:27], 0, v[134:135]
	v_lshl_add_u64 v[30:31], v[26:27], 0, v[132:133]
	global_load_dwordx4 v[2:5], v[4:5], off nt
	s_nop 0
	global_load_dwordx4 v[6:9], v[6:7], off nt
	s_nop 0
	global_load_dwordx4 v[10:13], v[12:13], off nt
	s_nop 0
	global_load_dwordx4 v[14:17], v[14:15], off nt
	s_nop 0
	global_load_dwordx4 v[18:21], v[20:21], off nt
	s_nop 0
	global_load_dwordx4 v[22:25], v[22:23], off nt
	s_nop 0
	global_load_dwordx4 v[26:29], v[28:29], off nt
	s_nop 0
	global_load_dwordx4 v[30:33], v[30:31], off nt
	v_and_b32_e32 v44, 7, v0
	v_lshrrev_b32_e32 v45, 6, v0
	v_bfe_u32 v46, v0, 3, 3
	v_lshlrev_b32_e32 v47, 9, v45
	v_lshlrev_b32_e32 v48, 2, v44
	v_add3_u32 v148, 0, v47, v48
	v_lshlrev_b32_e32 v47, 9, v46
	v_add3_u32 v149, 0, v47, v48
	v_mbcnt_lo_u32_b32 v47, -1, 0
	v_mbcnt_hi_u32_b32 v47, -1, v47
	s_movk_i32 s0, 0x80
	v_and_b32_e32 v49, 64, v47
	v_subrev_co_u32_e32 v134, vcc, s0, v0
	v_xor_b32_e32 v48, 1, v47
	v_add_u32_e32 v49, 64, v49
	s_xor_b64 s[10:11], vcc, -1
	v_cmp_lt_i32_e32 vcc, v48, v49
	v_add_u32_e32 v131, 0, v34
	v_lshrrev_b32_e32 v34, 3, v0
	v_cndmask_b32_e32 v48, v47, v48, vcc
	v_lshlrev_b32_e32 v150, 2, v48
	v_xor_b32_e32 v48, 2, v47
	v_cmp_lt_i32_e32 vcc, v48, v49
	v_lshl_add_u32 v153, v34, 2, 0
	v_and_b32_e32 v130, 0x7f, v0
	v_cndmask_b32_e32 v48, v47, v48, vcc
	v_lshlrev_b32_e32 v151, 2, v48
	v_xor_b32_e32 v48, 4, v47
	v_cmp_lt_i32_e32 vcc, v48, v49
	v_xor_b32_e32 v34, 8, v47
	v_cmp_eq_u32_e64 s[6:7], 0, v44
	v_cndmask_b32_e32 v48, v47, v48, vcc
	v_lshl_add_u32 v155, v130, 2, 0
	v_cmp_lt_i32_e32 vcc, v34, v49
	v_lshl_add_u32 v159, v36, 8, 0
	v_mul_i32_i24_e32 v44, 0xffffff20, v36
	v_and_b32_e32 v36, 0x180, v0
	v_cndmask_b32_e32 v34, v47, v34, vcc
	v_lshl_add_u32 v167, v36, 2, v155
	v_lshrrev_b32_e32 v36, 2, v0
	v_readlane_b32 s12, v238, 29
	v_lshlrev_b32_e32 v156, 2, v34
	v_xor_b32_e32 v34, 16, v47
	v_lshl_add_u32 v161, v38, 5, 0
	v_and_b32_e32 v38, 0x60, v36
	s_movk_i32 s3, 0x380
	v_mov_b32_e32 v36, 0x200
	v_readlane_b32 s13, v238, 30
	s_add_i32 s12, s2, s52
	v_cmp_lt_i32_e32 vcc, v34, v49
	v_bitop3_b32 v36, v0, s3, v36 bitop3:0xc8
	s_lshl_b32 s3, s96, 9
	s_ashr_i32 s13, s12, 31
	v_cndmask_b32_e32 v34, v47, v34, vcc
	s_add_i32 s3, s3, 0
	s_lshl_b64 s[12:13], s[12:13], 16
	v_lshlrev_b32_e32 v157, 2, v34
	v_xor_b32_e32 v34, 32, v47
	s_add_u32 s12, s68, s12
	v_cmp_lt_i32_e32 vcc, v34, v49
	v_lshl_add_u32 v169, v36, 2, v155
	v_lshlrev_b32_e32 v36, 3, v154
	s_addc_u32 s13, s69, s13
	v_cndmask_b32_e32 v34, v47, v34, vcc
	v_add_u32_e32 v171, s3, v36
	v_lshl_add_u64 v[140:141], s[12:13], 0, v[132:133]
	s_lshl_b64 s[12:13], s[52:53], 16
	s_lshl_b32 s3, s2, 1
	s_lshl_b32 s33, s52, 1
	v_lshlrev_b32_e32 v158, 2, v34
	v_or_b32_e32 v34, 0x200, v0
	v_lshl_add_u32 v160, v37, 5, 0
	v_mov_b32_e32 v37, v135
	v_readlane_b32 s14, v238, 31
	v_readlane_b32 s15, v238, 32
	s_add_u32 s4, s48, s4
	v_lshl_add_u32 v146, v0, 2, 0
	v_lshrrev_b32_e32 v34, 2, v34
	v_lshl_add_u64 v[136:137], s[14:15], 0, v[36:37]
	v_and_b32_e32 v36, 31, v0
	s_addc_u32 s5, s49, s5
	s_movk_i32 s0, 0x100
	v_mad_u32_u24 v147, v0, 28, v146
	v_mul_i32_i24_e32 v35, 0xffffffe4, v0
	v_lshl_add_u32 v162, v39, 5, 0
	v_and_b32_e32 v39, 0xe0, v34
	v_lshlrev_b32_e32 v34, 1, v154
	v_lshlrev_b32_e32 v138, 4, v36
	v_lshl_add_u64 v[36:37], s[4:5], 0, v[132:133]
	s_mov_b64 s[4:5], 0x4820800
	v_cmp_gt_u32_e64 s[0:1], s0, v0
	v_lshlrev_b32_e32 v152, 2, v48
	v_cmp_gt_u32_e64 s[8:9], v46, v45
	v_lshl_add_u32 v163, v40, 5, 0
	v_lshl_add_u32 v164, v41, 5, 0
	v_lshl_add_u32 v165, v42, 5, 0
	v_lshl_add_u32 v166, v43, 5, 0
	v_add_u32_e32 v168, 0x6300, v167
	v_add_u32_e32 v170, 0x6300, v169
	v_mov_b32_e32 v139, v135
	v_lshl_add_u64 v[142:143], v[36:37], 0, s[4:5]
	v_lshlrev_b64 v[144:145], 1, v[134:135]
	v_add_u32_e32 v133, v147, v35
	v_add_u32_e32 v172, v159, v44
	v_add_u32_e32 v173, 0, v38
	v_add_u32_e32 v174, 0, v39
	v_lshlrev_b32_e32 v134, 1, v34
	v_mov_b32_e32 v175, 0x358637bd
	s_mov_b32 s34, s2
	v_readlane_b32 s61, v238, 5
	v_readlane_b32 s62, v238, 6
	v_readlane_b32 s63, v238, 7
	v_readlane_b32 s64, v238, 8
	v_readlane_b32 s65, v238, 9
	v_readlane_b32 s66, v238, 10
	v_readlane_b32 s67, v238, 11
	v_readlane_b32 s70, v238, 14
	v_readlane_b32 s71, v238, 15
	v_readlane_b32 s72, v238, 16
	v_readlane_b32 s73, v238, 17
	v_readlane_b32 s74, v238, 18
	v_readlane_b32 s75, v238, 19
	v_readlane_b32 s16, v238, 33
	v_readlane_b32 s17, v238, 34
	v_readlane_b32 s18, v238, 35
	v_readlane_b32 s19, v238, 36
	v_readlane_b32 s20, v238, 37
	v_readlane_b32 s21, v238, 38
	v_readlane_b32 s22, v238, 39
	v_readlane_b32 s23, v238, 40
	v_readlane_b32 s24, v238, 41
	v_readlane_b32 s25, v238, 42
	v_readlane_b32 s26, v238, 43
	v_readlane_b32 s27, v238, 44
	s_branch .LBB0_280
